# first sub-tile: the four path-independent map-0 converts hoisted above the softmax trigger branch to fill the compare-to-branch latency
# baseline (speedup 1.0000x reference)
; __device__ __forceinline__ void dattn_unit(LAS unsigned char* lds, int b, int h, int qb, const bf16* Q, const bf16* K, const bf16* V, bf16* YB, float lam, const float* subg, float oml, int tid) {
;     ...
; #pragma unroll
;         for (int sub = 0; sub < 2; ++sub) {
;             if (kvbase + 32 * sub > qmax) continue;
;             const bool need_bm = kvbase + 32 * sub + 31 + 113 > qmin;
;             LAS bf16x8* qsp = qs; asm volatile("" : "+v"(qsp));
;             f32x16 s0, s1;
; #pragma unroll
;             for (int r = 0; r < 16; ++r) { s0[r] = -mref[0]; s1[r] = -mref[1]; }
;             {
;                 const LAS bf16* kp = Ks + (32 * sub + ql) * 72 + hi * 8;
;                 bf16x8 ka = *(const LAS bf16x8*)kp, kb = *(const LAS bf16x8*)(kp + 64 * 72), qa = qsp[0], qb = qsp[4 * 64];
;                 __builtin_amdgcn_sched_group_barrier(0x100, 4, 0);
; #pragma unroll
;                 for (int ks = 0; ks < 4; ++ks) { bf16x8 ka2 = ka, kb2 = kb, qa2 = qa, qb2 = qb;
;                     if (ks < 3) { ka2 = *(const LAS bf16x8*)(kp + (ks + 1) * 16); kb2 = *(const LAS bf16x8*)(kp + 64 * 72 + (ks + 1) * 16); qa2 = qsp[(ks + 1) * 64]; qb2 = qsp[(4 + ks + 1) * 64];
;                         __builtin_amdgcn_sched_group_barrier(0x100, 4, 0); }
;                     s0 = __builtin_amdgcn_mfma_f32_32x32x16_bf16(ka, qa, s0, 0, 0, 0);
;                     s1 = __builtin_amdgcn_mfma_f32_32x32x16_bf16(kb, qb, s1, 0, 0, 0);
;                     __builtin_amdgcn_sched_group_barrier(0x008, 2, 0);
;                     ka = ka2; kb = kb2; qa = qa2; qb = qb2; }
;             }
;             if (need_bm) { const LAS float* gb = tab + (159 - (q - (kvbase + 32 * sub + 4 * hi)));
; #pragma unroll
;                 for (int r = 0; r < 16; ++r) { const float bv = gb[(r & 3) + 8 * (r >> 2)]; s0[r] += bv; s1[r] += bv; } }
;             bf16x8 pA0, pB0, pA1, pB1; bool trig[2]; float pmx[2] = {1.f, 1.f};
;             AT_SOFTMAX(s0, 0, pA0, pB0);
;             AT_SOFTMAX(s1, 1, pA1, pB1);
; #pragma unroll
;             for (int cb = 0; cb < 4; ++cb) { const LAS bf16* vp = Vt + (32 * cb + ql) * 72 + 32 * sub + 4 * hi;
;                 const v2u a0 = *(const LAS v2u*)(vp), a1 = *(const LAS v2u*)(vp + 8), a2 = *(const LAS v2u*)(vp + 16), a3 = *(const LAS v2u*)(vp + 24);
;                 const v4u f0 = {a0.x, a0.y, a1.x, a1.y}, f1 = {a2.x, a2.y, a3.x, a3.y};
.Lsm0_0:
	v_exp_f32_e32 v201, v144
	v_exp_f32_e32 v202, v145
	v_exp_f32_e32 v203, v146
	v_exp_f32_e32 v204, v147
	v_exp_f32_e32 v205, v148
	v_add_f32_e32 v144, v202, v201
	v_exp_f32_e32 v206, v149
	v_add_f32_e32 v144, v203, v144
	v_exp_f32_e32 v207, v150
	v_add_f32_e32 v144, v204, v144
	v_exp_f32_e32 v218, v151
	v_add_f32_e32 v144, v205, v144
	v_exp_f32_e32 v147, v152
	v_add_f32_e32 v144, v206, v144
	v_exp_f32_e32 v148, v153
	v_add_f32_e32 v144, v207, v144
	v_exp_f32_e32 v149, v154
	v_add_f32_e32 v144, v218, v144
	v_exp_f32_e32 v150, v155
	v_add_f32_e32 v144, v147, v144
	v_exp_f32_e32 v151, v156
	v_add_f32_e32 v144, v148, v144
	v_exp_f32_e32 v152, v157
	v_add_f32_e32 v144, v149, v144
	v_exp_f32_e32 v153, v158
	v_add_f32_e32 v144, v150, v144
	v_exp_f32_e32 v154, v159
	v_add_f32_e32 v144, v151, v144
	v_add_f32_e32 v144, v152, v144
	v_add_f32_e32 v144, v153, v144
	v_add_f32_e32 v145, v154, v144
	v_cmp_lt_f32_e32 vcc, s82, v145
	s_mov_b64 s[48:49], 0
	v_cvt_pk_bf16_f32 v224, v201, v202
	v_cvt_pk_bf16_f32 v225, v203, v204
	v_cvt_pk_bf16_f32 v226, v205, v206
	v_cvt_pk_bf16_f32 v227, v207, v218
	s_cbranch_vccz .LBB0_232
	s_mov_b64 s[48:49], -1
	v_max_f32_e32 v146, v204, v204
	v_max_f32_e32 v155, v203, v203
	v_max_f32_e32 v146, v155, v146
	v_max_f32_e32 v155, v218, v218
	v_max_f32_e32 v156, v207, v207
	v_max_f32_e32 v155, v156, v155
	v_max_f32_e32 v156, v148, v148
	v_max_f32_e32 v157, v147, v147
	v_max_f32_e32 v156, v157, v156
	v_max_f32_e32 v157, v150, v150
	v_max_f32_e32 v158, v149, v149
	v_max_f32_e32 v157, v158, v157
	v_max_f32_e32 v158, v154, v154
	v_max_f32_e32 v159, v153, v153
	v_max_f32_e32 v158, v159, v158
	v_max3_f32 v158, v151, v152, v158
	v_max3_f32 v146, v201, v202, v146
	v_max3_f32 v155, v205, v206, v155
	v_max3_f32 v156, v156, v157, v158
	v_max3_f32 v146, v146, v155, v156
	v_mov_b32_e32 v155, v146
	s_nop 1
	v_permlane32_swap_b32_e32 v146, v155
	v_max_f32_e32 v155, v155, v155
	v_max_f32_e32 v146, v146, v146
	v_max_f32_e32 v146, v146, v155
.LBB0_232:
	ds_read_b128 v[204:207], v219 offset:18464
	ds_read_b128 v[200:203], v219 offset:32288
	v_cvt_pk_bf16_f32 v148, v147, v148
	v_cvt_pk_bf16_f32 v149, v149, v150
	s_waitcnt lgkmcnt(2)
	v_mfma_f32_32x32x16_bf16 v[80:95], v[228:231], v[224:227], v[80:95]
	v_cvt_pk_bf16_f32 v150, v151, v152
	v_cvt_pk_bf16_f32 v151, v153, v154
	v_add_f32_e32 v179, v179, v145
	v_exp_f32_e32 v155, v128
	v_exp_f32_e32 v129, v129
	v_exp_f32_e32 v130, v130
	v_exp_f32_e32 v131, v131
	v_exp_f32_e32 v132, v132
	v_add_f32_e32 v128, v129, v155
	v_exp_f32_e32 v156, v133
	v_mfma_f32_32x32x16_bf16 v[80:95], v[232:235], v[148:151], v[80:95]
	v_add_f32_e32 v128, v130, v128
	v_exp_f32_e32 v157, v134
	v_add_f32_e32 v128, v131, v128
	v_exp_f32_e32 v158, v135
	v_mfma_f32_32x32x16_bf16 v[48:63], v[236:239], v[224:227], v[48:63]
	v_add_f32_e32 v128, v132, v128
	v_exp_f32_e32 v133, v136
	v_add_f32_e32 v128, v156, v128
	v_exp_f32_e32 v134, v137
	v_mfma_f32_32x32x16_bf16 v[48:63], v[240:243], v[148:151], v[48:63]
	v_add_f32_e32 v128, v157, v128
	v_exp_f32_e32 v135, v138
	v_add_f32_e32 v128, v158, v128
	v_exp_f32_e32 v136, v139
	v_mfma_f32_32x32x16_bf16 v[16:31], v[212:215], v[224:227], v[16:31]
	v_add_f32_e32 v128, v133, v128
	v_exp_f32_e32 v137, v140
	v_add_f32_e32 v128, v134, v128
	v_exp_f32_e32 v138, v141
	v_mfma_f32_32x32x16_bf16 v[112:127], v[220:223], v[224:227], v[112:127]
	v_add_f32_e32 v128, v135, v128
	v_exp_f32_e32 v139, v142
	v_add_f32_e32 v128, v136, v128
	v_exp_f32_e32 v140, v143
	s_waitcnt lgkmcnt(1)
	v_mfma_f32_32x32x16_bf16 v[112:127], v[204:207], v[148:151], v[112:127]
	v_add_f32_e32 v128, v137, v128
	v_add_f32_e32 v128, v138, v128
	v_add_f32_e32 v128, v139, v128
	v_add_f32_e32 v128, v140, v128
	s_waitcnt lgkmcnt(0)
	v_mfma_f32_32x32x16_bf16 v[16:31], v[200:203], v[148:151], v[16:31]
	v_cmp_lt_f32_e32 vcc, s82, v128
	s_mov_b64 s[46:47], 0
	s_cbranch_vccz .LBB0_234
	s_mov_b64 s[46:47], -1
	v_max_f32_e32 v141, v131, v131
	v_max_f32_e32 v142, v130, v130
	v_max_f32_e32 v141, v142, v141
	v_max_f32_e32 v142, v158, v158
	v_max_f32_e32 v143, v157, v157
	v_max_f32_e32 v142, v143, v142
	v_max_f32_e32 v143, v134, v134
	v_max_f32_e32 v144, v133, v133
	v_max_f32_e32 v143, v144, v143
	v_max_f32_e32 v144, v136, v136
	v_max_f32_e32 v159, v135, v135
	v_max_f32_e32 v144, v159, v144
	v_max_f32_e32 v159, v140, v140
	v_max_f32_e32 v147, v139, v139
	v_max_f32_e32 v159, v147, v159
	v_max3_f32 v159, v137, v138, v159
	v_max3_f32 v141, v155, v129, v141
	v_max3_f32 v142, v132, v156, v142
	v_max3_f32 v143, v143, v144, v159
	v_max3_f32 v141, v141, v142, v143
	v_mov_b32_e32 v142, v141
	s_nop 1
	v_permlane32_swap_b32_e32 v141, v142
	v_max_f32_e32 v142, v142, v142
	v_max_f32_e32 v141, v141, v141
	v_max_f32_e32 v144, v141, v142
